# plus phase 11 SwiGLU epilogue with fewer VALU instructions per row (f32 throughout, products reassociated: (g*u)*rs^2*sigmoid(g*rs))
# speedup vs baseline: 1.0104x; 1.0069x over previous
; __device__ __forceinline__ unsigned cvt_pk_bf16(float lo, float hi) { cvf32x2_t v = {lo, hi}; cvbf16x2_t b = __builtin_convertvector(v, cvbf16x2_t); return __builtin_bit_cast(unsigned, b); }
; __device__ __forceinline__ float fsigm(float x) { return __builtin_amdgcn_rcpf(1.f + __expf(-x)); }
; __device__ __forceinline__ float fsilu(float x) { return x * fsigm(x); }
; __device__ __forceinline__ float row_rs(const float* ssq, int row) { return ssq ? rsqrtf(ssq[row] * (1.f / 1024.f) + RMS_EPS) : 1.f; }
;     __device__ __forceinline__ void operator()(const f32x4 (&acc)[2][2][4][2], const Unit& u, int wr, int wc, int fr, int fq) const {
;     ...
;             for (int m = 0; m < 4; ++m) { const int row = row0 + ai * HALF + m * 16; const float rs = row_rs(ssq, row);
;                 u32x4 w; unsigned pk[4];
; #pragma unroll
;                 for (int n = 0; n < 2; ++n) { const f32x4 g = acc[ai][0][m][n] * rs, up = acc[ai][1][m][n] * rs;
;                     pk[2 * n] = cvt_pk_bf16(fsilu(g[0]) * up[0], fsilu(g[1]) * up[1]); pk[2 * n + 1] = cvt_pk_bf16(fsilu(g[2]) * up[2], fsilu(g[3]) * up[3]); }
;                 w.x = pk[0]; w.y = pk[1]; w.z = pk[2]; w.w = pk[3];
;                 st_wt16(H + (size_t)row * ldh + col0, w); }
.LBB0_1274:
	v_lshl_add_u32 v144, s6, 8, v152
	v_ashrrev_i32_e32 v145, 31, v144
	v_lshl_add_u64 v[150:151], v[144:145], 2, s[12:13]
	global_load_dword v145, v[150:151], off
	global_load_dword v176, v[150:151], off offset:64
	global_load_dword v177, v[150:151], off offset:128
	global_load_dword v178, v[150:151], off offset:192
	global_load_dword v179, v[150:151], off offset:512
	global_load_dword v180, v[150:151], off offset:576
	global_load_dword v181, v[150:151], off offset:640
	global_load_dword v182, v[150:151], off offset:704
	v_or_b32_e32 v162, 16, v144
	v_ashrrev_i32_e32 v163, 31, v162
	v_lshl_add_u64 v[164:165], v[162:163], 2, s[12:13]
	v_lshl_or_b32 v148, s7, 7, v154
	v_mov_b64_e32 v[146:147], s[56:57]
	v_ashrrev_i32_e32 v149, 31, v148
	v_mad_i64_i32 v[160:161], s[6:7], v144, s79, v[146:147]
	v_lshlrev_b64 v[148:149], 1, v[148:149]
	v_lshl_add_u64 v[160:161], v[160:161], 0, v[148:149]
	s_waitcnt vmcnt(0)
	v_fmamk_f32 v145, v145, 0x3a800000, v158
	v_mul_f32_e32 v159, 0x4b800000, v145
	v_cmp_gt_f32_e32 vcc, s77, v145
	s_nop 1
	v_cndmask_b32_e32 v145, v145, v159, vcc
	v_rsq_f32_e32 v145, v145
	s_nop 0
	v_mul_f32_e32 v159, 0x45800000, v145
	v_cndmask_b32_e32 v166, v145, v159, vcc
	v_mov_b32_e32 v192, 1.0
	v_mul_f32_e32 v188, 0xbfb8aa3b, v166
	v_mul_f32_e32 v190, v166, v166
	v_pk_mul_f32 v[184:185], v[124:125], v[188:189] op_sel_hi:[1,0]
	v_pk_mul_f32 v[186:187], v[126:127], v[188:189] op_sel_hi:[1,0]
	v_pk_mul_f32 v[124:125], v[124:125], v[116:117]
	v_exp_f32_e32 v184, v184
	v_exp_f32_e32 v185, v185
	v_exp_f32_e32 v186, v186
	v_exp_f32_e32 v187, v187
	v_pk_mul_f32 v[126:127], v[126:127], v[118:119]
	v_pk_add_f32 v[184:185], v[184:185], v[192:193] op_sel_hi:[1,0]
	v_pk_add_f32 v[186:187], v[186:187], v[192:193] op_sel_hi:[1,0]
	v_rcp_f32_e32 v184, v184
	v_rcp_f32_e32 v185, v185
	v_rcp_f32_e32 v186, v186
	v_rcp_f32_e32 v187, v187
	v_pk_mul_f32 v[124:125], v[124:125], v[190:191] op_sel_hi:[1,0]
	v_pk_mul_f32 v[126:127], v[126:127], v[190:191] op_sel_hi:[1,0]
	v_pk_mul_f32 v[124:125], v[124:125], v[184:185]
	v_pk_mul_f32 v[126:127], v[126:127], v[186:187]
	v_pk_mul_f32 v[184:185], v[120:121], v[188:189] op_sel_hi:[1,0]
	v_pk_mul_f32 v[186:187], v[122:123], v[188:189] op_sel_hi:[1,0]
	v_pk_mul_f32 v[120:121], v[120:121], v[112:113]
	v_exp_f32_e32 v184, v184
	v_exp_f32_e32 v185, v185
	v_exp_f32_e32 v186, v186
	v_exp_f32_e32 v187, v187
	v_pk_mul_f32 v[122:123], v[122:123], v[114:115]
	v_pk_add_f32 v[184:185], v[184:185], v[192:193] op_sel_hi:[1,0]
	v_pk_add_f32 v[186:187], v[186:187], v[192:193] op_sel_hi:[1,0]
	v_rcp_f32_e32 v184, v184
	v_rcp_f32_e32 v185, v185
	v_rcp_f32_e32 v186, v186
	v_rcp_f32_e32 v187, v187
	v_pk_mul_f32 v[120:121], v[120:121], v[190:191] op_sel_hi:[1,0]
	v_pk_mul_f32 v[122:123], v[122:123], v[190:191] op_sel_hi:[1,0]
	v_pk_mul_f32 v[120:121], v[120:121], v[184:185]
	v_pk_mul_f32 v[122:123], v[122:123], v[186:187]
	v_cvt_pk_bf16_f32 v112, v124, v125
	v_cvt_pk_bf16_f32 v113, v126, v127
	v_cvt_pk_bf16_f32 v114, v120, v121
	v_cvt_pk_bf16_f32 v115, v122, v123
	s_nop 0
	global_store_dwordx4 v[160:161], v[112:115], off
	s_nop 1
	s_nop 0
	v_or_b32_e32 v112, 32, v144
	v_mad_i64_i32 v[114:115], s[6:7], v162, s79, v[146:147]
	v_lshl_add_u64 v[114:115], v[114:115], 0, v[148:149]
	v_fmamk_f32 v113, v176, 0x3a800000, v158
	v_mul_f32_e32 v116, 0x4b800000, v113
	v_cmp_gt_f32_e32 vcc, s77, v113
	s_nop 1
	v_cndmask_b32_e32 v113, v113, v116, vcc
	v_rsq_f32_e32 v118, v113
	v_ashrrev_i32_e32 v113, 31, v112
	v_lshl_add_u64 v[116:117], v[112:113], 2, s[12:13]
	v_mul_f32_e32 v113, 0x45800000, v118
	v_cndmask_b32_e32 v118, v118, v113, vcc
	v_mul_f32_e32 v188, 0xbfb8aa3b, v118
	v_mul_f32_e32 v190, v118, v118
	v_pk_mul_f32 v[184:185], v[108:109], v[188:189] op_sel_hi:[1,0]
	v_pk_mul_f32 v[186:187], v[110:111], v[188:189] op_sel_hi:[1,0]
	v_pk_mul_f32 v[108:109], v[108:109], v[100:101]
	v_exp_f32_e32 v184, v184
	v_exp_f32_e32 v185, v185
	v_exp_f32_e32 v186, v186
	v_exp_f32_e32 v187, v187
	v_pk_mul_f32 v[110:111], v[110:111], v[102:103]
	v_pk_add_f32 v[184:185], v[184:185], v[192:193] op_sel_hi:[1,0]
	v_pk_add_f32 v[186:187], v[186:187], v[192:193] op_sel_hi:[1,0]
	v_rcp_f32_e32 v184, v184
	v_rcp_f32_e32 v185, v185
	v_rcp_f32_e32 v186, v186
	v_rcp_f32_e32 v187, v187
	v_pk_mul_f32 v[108:109], v[108:109], v[190:191] op_sel_hi:[1,0]
	v_pk_mul_f32 v[110:111], v[110:111], v[190:191] op_sel_hi:[1,0]
	v_pk_mul_f32 v[108:109], v[108:109], v[184:185]
	v_pk_mul_f32 v[110:111], v[110:111], v[186:187]
	v_pk_mul_f32 v[184:185], v[104:105], v[188:189] op_sel_hi:[1,0]
	v_pk_mul_f32 v[186:187], v[106:107], v[188:189] op_sel_hi:[1,0]
	v_pk_mul_f32 v[104:105], v[104:105], v[96:97]
	v_exp_f32_e32 v184, v184
	v_exp_f32_e32 v185, v185
	v_exp_f32_e32 v186, v186
	v_exp_f32_e32 v187, v187
	v_pk_mul_f32 v[106:107], v[106:107], v[98:99]
	v_pk_add_f32 v[184:185], v[184:185], v[192:193] op_sel_hi:[1,0]
	v_pk_add_f32 v[186:187], v[186:187], v[192:193] op_sel_hi:[1,0]
	v_rcp_f32_e32 v184, v184
	v_rcp_f32_e32 v185, v185
	v_rcp_f32_e32 v186, v186
	v_rcp_f32_e32 v187, v187
	v_pk_mul_f32 v[104:105], v[104:105], v[190:191] op_sel_hi:[1,0]
	v_pk_mul_f32 v[106:107], v[106:107], v[190:191] op_sel_hi:[1,0]
	v_pk_mul_f32 v[104:105], v[104:105], v[184:185]
	v_pk_mul_f32 v[106:107], v[106:107], v[186:187]
	v_cvt_pk_bf16_f32 v96, v108, v109
	v_cvt_pk_bf16_f32 v97, v110, v111
	v_cvt_pk_bf16_f32 v98, v104, v105
	v_cvt_pk_bf16_f32 v99, v106, v107
	s_nop 0
	global_store_dwordx4 v[114:115], v[96:99], off
	s_nop 1
	s_nop 0
	v_or_b32_e32 v96, 48, v144
	v_mad_i64_i32 v[98:99], s[6:7], v112, s79, v[146:147]
	v_lshl_add_u64 v[98:99], v[98:99], 0, v[148:149]
	v_fmamk_f32 v97, v177, 0x3a800000, v158
; __device__ __forceinline__ unsigned cvt_pk_bf16(float lo, float hi) { cvf32x2_t v = {lo, hi}; cvbf16x2_t b = __builtin_convertvector(v, cvbf16x2_t); return __builtin_bit_cast(unsigned, b); }
; __device__ __forceinline__ float fsigm(float x) { return __builtin_amdgcn_rcpf(1.f + __expf(-x)); }
; __device__ __forceinline__ float fsilu(float x) { return x * fsigm(x); }
; __device__ __forceinline__ float row_rs(const float* ssq, int row) { return ssq ? rsqrtf(ssq[row] * (1.f / 1024.f) + RMS_EPS) : 1.f; }
;     __device__ __forceinline__ void operator()(const f32x4 (&acc)[2][2][4][2], const Unit& u, int wr, int wc, int fr, int fq) const {
;     ...
;             for (int m = 0; m < 4; ++m) { const int row = row0 + ai * HALF + m * 16; const float rs = row_rs(ssq, row);
;                 u32x4 w; unsigned pk[4];
; #pragma unroll
;                 for (int n = 0; n < 2; ++n) { const f32x4 g = acc[ai][0][m][n] * rs, up = acc[ai][1][m][n] * rs;
;                     pk[2 * n] = cvt_pk_bf16(fsilu(g[0]) * up[0], fsilu(g[1]) * up[1]); pk[2 * n + 1] = cvt_pk_bf16(fsilu(g[2]) * up[2], fsilu(g[3]) * up[3]); }
;                 w.x = pk[0]; w.y = pk[1]; w.z = pk[2]; w.w = pk[3];
;                 st_wt16(H + (size_t)row * ldh + col0, w); }
	v_mul_f32_e32 v100, 0x4b800000, v97
	v_cmp_gt_f32_e32 vcc, s77, v97
	s_nop 1
	v_cndmask_b32_e32 v97, v97, v100, vcc
	v_rsq_f32_e32 v102, v97
	v_ashrrev_i32_e32 v97, 31, v96
	v_lshl_add_u64 v[100:101], v[96:97], 2, s[12:13]
	v_mul_f32_e32 v97, 0x45800000, v102
	v_cndmask_b32_e32 v102, v102, v97, vcc
	v_mul_f32_e32 v188, 0xbfb8aa3b, v102
	v_mul_f32_e32 v190, v102, v102
	v_pk_mul_f32 v[184:185], v[92:93], v[188:189] op_sel_hi:[1,0]
	v_pk_mul_f32 v[186:187], v[94:95], v[188:189] op_sel_hi:[1,0]
	v_pk_mul_f32 v[92:93], v[92:93], v[84:85]
	v_exp_f32_e32 v184, v184
	v_exp_f32_e32 v185, v185
	v_exp_f32_e32 v186, v186
	v_exp_f32_e32 v187, v187
	v_pk_mul_f32 v[94:95], v[94:95], v[86:87]
	v_pk_add_f32 v[184:185], v[184:185], v[192:193] op_sel_hi:[1,0]
	v_pk_add_f32 v[186:187], v[186:187], v[192:193] op_sel_hi:[1,0]
	v_rcp_f32_e32 v184, v184
	v_rcp_f32_e32 v185, v185
	v_rcp_f32_e32 v186, v186
	v_rcp_f32_e32 v187, v187
	v_pk_mul_f32 v[92:93], v[92:93], v[190:191] op_sel_hi:[1,0]
	v_pk_mul_f32 v[94:95], v[94:95], v[190:191] op_sel_hi:[1,0]
	v_pk_mul_f32 v[92:93], v[92:93], v[184:185]
	v_pk_mul_f32 v[94:95], v[94:95], v[186:187]
	v_pk_mul_f32 v[184:185], v[88:89], v[188:189] op_sel_hi:[1,0]
	v_pk_mul_f32 v[186:187], v[90:91], v[188:189] op_sel_hi:[1,0]
	v_pk_mul_f32 v[88:89], v[88:89], v[80:81]
	v_exp_f32_e32 v184, v184
	v_exp_f32_e32 v185, v185
	v_exp_f32_e32 v186, v186
	v_exp_f32_e32 v187, v187
	v_pk_mul_f32 v[90:91], v[90:91], v[82:83]
	v_pk_add_f32 v[184:185], v[184:185], v[192:193] op_sel_hi:[1,0]
	v_pk_add_f32 v[186:187], v[186:187], v[192:193] op_sel_hi:[1,0]
	v_rcp_f32_e32 v184, v184
	v_rcp_f32_e32 v185, v185
	v_rcp_f32_e32 v186, v186
	v_rcp_f32_e32 v187, v187
	v_pk_mul_f32 v[88:89], v[88:89], v[190:191] op_sel_hi:[1,0]
	v_pk_mul_f32 v[90:91], v[90:91], v[190:191] op_sel_hi:[1,0]
	v_pk_mul_f32 v[88:89], v[88:89], v[184:185]
	v_pk_mul_f32 v[90:91], v[90:91], v[186:187]
	v_cvt_pk_bf16_f32 v80, v92, v93
	v_cvt_pk_bf16_f32 v81, v94, v95
	v_cvt_pk_bf16_f32 v82, v88, v89
	v_cvt_pk_bf16_f32 v83, v90, v91
	s_nop 0
	global_store_dwordx4 v[98:99], v[80:83], off
	s_nop 1
	v_fmamk_f32 v80, v178, 0x3a800000, v158
	v_mul_f32_e32 v81, 0x4b800000, v80
	v_cmp_gt_f32_e32 vcc, s77, v80
	s_nop 1
	v_cndmask_b32_e32 v80, v80, v81, vcc
	v_rsq_f32_e32 v82, v80
	v_mad_i64_i32 v[80:81], s[6:7], v96, s79, v[146:147]
	v_lshl_add_u64 v[80:81], v[80:81], 0, v[148:149]
	v_mul_f32_e32 v83, 0x45800000, v82
	v_cndmask_b32_e32 v82, v82, v83, vcc
	v_mul_f32_e32 v188, 0xbfb8aa3b, v82
	v_mul_f32_e32 v190, v82, v82
	v_pk_mul_f32 v[184:185], v[76:77], v[188:189] op_sel_hi:[1,0]
	v_pk_mul_f32 v[186:187], v[78:79], v[188:189] op_sel_hi:[1,0]
	v_pk_mul_f32 v[76:77], v[76:77], v[68:69]
	v_exp_f32_e32 v184, v184
	v_exp_f32_e32 v185, v185
	v_exp_f32_e32 v186, v186
	v_exp_f32_e32 v187, v187
	v_pk_mul_f32 v[78:79], v[78:79], v[70:71]
	v_pk_add_f32 v[184:185], v[184:185], v[192:193] op_sel_hi:[1,0]
	v_pk_add_f32 v[186:187], v[186:187], v[192:193] op_sel_hi:[1,0]
	v_rcp_f32_e32 v184, v184
	v_rcp_f32_e32 v185, v185
	v_rcp_f32_e32 v186, v186
	v_rcp_f32_e32 v187, v187
	v_pk_mul_f32 v[76:77], v[76:77], v[190:191] op_sel_hi:[1,0]
	v_pk_mul_f32 v[78:79], v[78:79], v[190:191] op_sel_hi:[1,0]
	v_pk_mul_f32 v[76:77], v[76:77], v[184:185]
	v_pk_mul_f32 v[78:79], v[78:79], v[186:187]
	v_pk_mul_f32 v[184:185], v[72:73], v[188:189] op_sel_hi:[1,0]
	v_pk_mul_f32 v[186:187], v[74:75], v[188:189] op_sel_hi:[1,0]
	v_pk_mul_f32 v[72:73], v[72:73], v[64:65]
	v_exp_f32_e32 v184, v184
	v_exp_f32_e32 v185, v185
	v_exp_f32_e32 v186, v186
	v_exp_f32_e32 v187, v187
	v_pk_mul_f32 v[74:75], v[74:75], v[66:67]
	v_pk_add_f32 v[184:185], v[184:185], v[192:193] op_sel_hi:[1,0]
	v_pk_add_f32 v[186:187], v[186:187], v[192:193] op_sel_hi:[1,0]
	v_rcp_f32_e32 v184, v184
	v_rcp_f32_e32 v185, v185
	v_rcp_f32_e32 v186, v186
	v_rcp_f32_e32 v187, v187
	v_pk_mul_f32 v[72:73], v[72:73], v[190:191] op_sel_hi:[1,0]
	v_pk_mul_f32 v[74:75], v[74:75], v[190:191] op_sel_hi:[1,0]
	v_pk_mul_f32 v[72:73], v[72:73], v[184:185]
	v_pk_mul_f32 v[74:75], v[74:75], v[186:187]
	v_cvt_pk_bf16_f32 v64, v76, v77
	v_cvt_pk_bf16_f32 v65, v78, v79
	v_cvt_pk_bf16_f32 v66, v72, v73
	v_cvt_pk_bf16_f32 v67, v74, v75
	s_nop 0
	global_store_dwordx4 v[80:81], v[64:67], off
	s_nop 1
	s_nop 0
	v_add_u32_e32 v65, 0x80, v144
	v_fmamk_f32 v64, v179, 0x3a800000, v158
	v_mul_f32_e32 v66, 0x4b800000, v64
	v_cmp_gt_f32_e32 vcc, s77, v64
	s_nop 1
	v_cndmask_b32_e32 v64, v64, v66, vcc
	v_rsq_f32_e32 v66, v64
	v_mad_i64_i32 v[64:65], s[6:7], v65, s79, v[146:147]
	v_lshl_add_u64 v[64:65], v[64:65], 0, v[148:149]
	v_mul_f32_e32 v67, 0x45800000, v66
	v_cndmask_b32_e32 v66, v66, v67, vcc
	v_mul_f32_e32 v188, 0xbfb8aa3b, v66
	v_mul_f32_e32 v190, v66, v66
	v_pk_mul_f32 v[184:185], v[60:61], v[188:189] op_sel_hi:[1,0]
	v_pk_mul_f32 v[186:187], v[62:63], v[188:189] op_sel_hi:[1,0]
	v_pk_mul_f32 v[60:61], v[60:61], v[52:53]
	v_exp_f32_e32 v184, v184
	v_exp_f32_e32 v185, v185
	v_exp_f32_e32 v186, v186
	v_exp_f32_e32 v187, v187
	v_pk_mul_f32 v[62:63], v[62:63], v[54:55]
	v_pk_add_f32 v[184:185], v[184:185], v[192:193] op_sel_hi:[1,0]
	v_pk_add_f32 v[186:187], v[186:187], v[192:193] op_sel_hi:[1,0]
	v_rcp_f32_e32 v184, v184
	v_rcp_f32_e32 v185, v185
	v_rcp_f32_e32 v186, v186
	v_rcp_f32_e32 v187, v187
	v_pk_mul_f32 v[60:61], v[60:61], v[190:191] op_sel_hi:[1,0]
	v_pk_mul_f32 v[62:63], v[62:63], v[190:191] op_sel_hi:[1,0]
	v_pk_mul_f32 v[60:61], v[60:61], v[184:185]
	v_pk_mul_f32 v[62:63], v[62:63], v[186:187]
	v_pk_mul_f32 v[184:185], v[56:57], v[188:189] op_sel_hi:[1,0]
	v_pk_mul_f32 v[186:187], v[58:59], v[188:189] op_sel_hi:[1,0]
	v_pk_mul_f32 v[56:57], v[56:57], v[48:49]
; __device__ __forceinline__ unsigned cvt_pk_bf16(float lo, float hi) { cvf32x2_t v = {lo, hi}; cvbf16x2_t b = __builtin_convertvector(v, cvbf16x2_t); return __builtin_bit_cast(unsigned, b); }
; __device__ __forceinline__ float fsigm(float x) { return __builtin_amdgcn_rcpf(1.f + __expf(-x)); }
; __device__ __forceinline__ float fsilu(float x) { return x * fsigm(x); }
; __device__ __forceinline__ float row_rs(const float* ssq, int row) { return ssq ? rsqrtf(ssq[row] * (1.f / 1024.f) + RMS_EPS) : 1.f; }
;     __device__ __forceinline__ void operator()(const f32x4 (&acc)[2][2][4][2], const Unit& u, int wr, int wc, int fr, int fq) const {
;     ...
;             for (int m = 0; m < 4; ++m) { const int row = row0 + ai * HALF + m * 16; const float rs = row_rs(ssq, row);
;                 u32x4 w; unsigned pk[4];
; #pragma unroll
;                 for (int n = 0; n < 2; ++n) { const f32x4 g = acc[ai][0][m][n] * rs, up = acc[ai][1][m][n] * rs;
;                     pk[2 * n] = cvt_pk_bf16(fsilu(g[0]) * up[0], fsilu(g[1]) * up[1]); pk[2 * n + 1] = cvt_pk_bf16(fsilu(g[2]) * up[2], fsilu(g[3]) * up[3]); }
;                 w.x = pk[0]; w.y = pk[1]; w.z = pk[2]; w.w = pk[3];
;                 st_wt16(H + (size_t)row * ldh + col0, w); }
	v_exp_f32_e32 v184, v184
	v_exp_f32_e32 v185, v185
	v_exp_f32_e32 v186, v186
	v_exp_f32_e32 v187, v187
	v_pk_mul_f32 v[58:59], v[58:59], v[50:51]
	v_pk_add_f32 v[184:185], v[184:185], v[192:193] op_sel_hi:[1,0]
	v_pk_add_f32 v[186:187], v[186:187], v[192:193] op_sel_hi:[1,0]
	v_rcp_f32_e32 v184, v184
	v_rcp_f32_e32 v185, v185
	v_rcp_f32_e32 v186, v186
	v_rcp_f32_e32 v187, v187
	v_pk_mul_f32 v[56:57], v[56:57], v[190:191] op_sel_hi:[1,0]
	v_pk_mul_f32 v[58:59], v[58:59], v[190:191] op_sel_hi:[1,0]
	v_pk_mul_f32 v[56:57], v[56:57], v[184:185]
	v_pk_mul_f32 v[58:59], v[58:59], v[186:187]
	v_cvt_pk_bf16_f32 v48, v60, v61
	v_cvt_pk_bf16_f32 v49, v62, v63
	v_cvt_pk_bf16_f32 v50, v56, v57
	v_cvt_pk_bf16_f32 v51, v58, v59
	s_nop 0
	global_store_dwordx4 v[64:65], v[48:51], off
	s_nop 1
	s_nop 0
	v_add_u32_e32 v49, 0x90, v144
	v_fmamk_f32 v48, v180, 0x3a800000, v158
	v_mul_f32_e32 v50, 0x4b800000, v48
	v_cmp_gt_f32_e32 vcc, s77, v48
	s_nop 1
	v_cndmask_b32_e32 v48, v48, v50, vcc
	v_rsq_f32_e32 v50, v48
	v_mad_i64_i32 v[48:49], s[6:7], v49, s79, v[146:147]
	v_lshl_add_u64 v[48:49], v[48:49], 0, v[148:149]
	v_mul_f32_e32 v51, 0x45800000, v50
	v_cndmask_b32_e32 v50, v50, v51, vcc
	v_mul_f32_e32 v188, 0xbfb8aa3b, v50
	v_mul_f32_e32 v190, v50, v50
	v_pk_mul_f32 v[184:185], v[44:45], v[188:189] op_sel_hi:[1,0]
	v_pk_mul_f32 v[186:187], v[46:47], v[188:189] op_sel_hi:[1,0]
	v_pk_mul_f32 v[44:45], v[44:45], v[36:37]
	v_exp_f32_e32 v184, v184
	v_exp_f32_e32 v185, v185
	v_exp_f32_e32 v186, v186
	v_exp_f32_e32 v187, v187
	v_pk_mul_f32 v[46:47], v[46:47], v[38:39]
	v_pk_add_f32 v[184:185], v[184:185], v[192:193] op_sel_hi:[1,0]
	v_pk_add_f32 v[186:187], v[186:187], v[192:193] op_sel_hi:[1,0]
	v_rcp_f32_e32 v184, v184
	v_rcp_f32_e32 v185, v185
	v_rcp_f32_e32 v186, v186
	v_rcp_f32_e32 v187, v187
	v_pk_mul_f32 v[44:45], v[44:45], v[190:191] op_sel_hi:[1,0]
	v_pk_mul_f32 v[46:47], v[46:47], v[190:191] op_sel_hi:[1,0]
	v_pk_mul_f32 v[44:45], v[44:45], v[184:185]
	v_pk_mul_f32 v[46:47], v[46:47], v[186:187]
	v_pk_mul_f32 v[184:185], v[40:41], v[188:189] op_sel_hi:[1,0]
	v_pk_mul_f32 v[186:187], v[42:43], v[188:189] op_sel_hi:[1,0]
	v_pk_mul_f32 v[40:41], v[40:41], v[32:33]
	v_exp_f32_e32 v184, v184
	v_exp_f32_e32 v185, v185
	v_exp_f32_e32 v186, v186
	v_exp_f32_e32 v187, v187
	v_pk_mul_f32 v[42:43], v[42:43], v[34:35]
	v_pk_add_f32 v[184:185], v[184:185], v[192:193] op_sel_hi:[1,0]
	v_pk_add_f32 v[186:187], v[186:187], v[192:193] op_sel_hi:[1,0]
	v_rcp_f32_e32 v184, v184
	v_rcp_f32_e32 v185, v185
	v_rcp_f32_e32 v186, v186
	v_rcp_f32_e32 v187, v187
	v_pk_mul_f32 v[40:41], v[40:41], v[190:191] op_sel_hi:[1,0]
	v_pk_mul_f32 v[42:43], v[42:43], v[190:191] op_sel_hi:[1,0]
	v_pk_mul_f32 v[40:41], v[40:41], v[184:185]
	v_pk_mul_f32 v[42:43], v[42:43], v[186:187]
	v_cvt_pk_bf16_f32 v32, v44, v45
	v_cvt_pk_bf16_f32 v33, v46, v47
	v_cvt_pk_bf16_f32 v34, v40, v41
	v_cvt_pk_bf16_f32 v35, v42, v43
	s_nop 0
	global_store_dwordx4 v[48:49], v[32:35], off
	s_nop 1
	s_nop 0
	v_add_u32_e32 v33, 0xa0, v144
	v_fmamk_f32 v32, v181, 0x3a800000, v158
	v_mul_f32_e32 v34, 0x4b800000, v32
	v_cmp_gt_f32_e32 vcc, s77, v32
	s_nop 1
	v_cndmask_b32_e32 v32, v32, v34, vcc
	v_rsq_f32_e32 v34, v32
	v_mad_i64_i32 v[32:33], s[6:7], v33, s79, v[146:147]
	v_lshl_add_u64 v[32:33], v[32:33], 0, v[148:149]
	v_mul_f32_e32 v35, 0x45800000, v34
	v_cndmask_b32_e32 v34, v34, v35, vcc
	v_mul_f32_e32 v188, 0xbfb8aa3b, v34
	v_mul_f32_e32 v190, v34, v34
	v_pk_mul_f32 v[184:185], v[28:29], v[188:189] op_sel_hi:[1,0]
	v_pk_mul_f32 v[186:187], v[30:31], v[188:189] op_sel_hi:[1,0]
	v_pk_mul_f32 v[28:29], v[28:29], v[20:21]
	v_exp_f32_e32 v184, v184
	v_exp_f32_e32 v185, v185
	v_exp_f32_e32 v186, v186
	v_exp_f32_e32 v187, v187
	v_pk_mul_f32 v[30:31], v[30:31], v[22:23]
; __device__ __forceinline__ unsigned cvt_pk_bf16(float lo, float hi) { cvf32x2_t v = {lo, hi}; cvbf16x2_t b = __builtin_convertvector(v, cvbf16x2_t); return __builtin_bit_cast(unsigned, b); }
; #define PG8_BAR __builtin_amdgcn_s_barrier()
; __device__ __forceinline__ float fsilu(float x) { return x * fsigm(x); }
; __device__ __forceinline__ float row_rs(const float* ssq, int row) { return ssq ? rsqrtf(ssq[row] * (1.f / 1024.f) + RMS_EPS) : 1.f; }
; template <class Epi, class Sched, bool ALIGN_EPI = false, bool SP2 = false>
; __device__ __forceinline__ void gemm_phase(PG8_LAS unsigned char* lds, const Gemm g, const Sched& S, const Epi& E) {
;     ...
;         if constexpr (ALIGN_EPI) { if (wr == 1) PG8_BAR; }
;     }
;     __device__ __forceinline__ void operator()(const f32x4 (&acc)[2][2][4][2], const Unit& u, int wr, int wc, int fr, int fq) const {
;     ...
;             for (int m = 0; m < 4; ++m) { const int row = row0 + ai * HALF + m * 16; const float rs = row_rs(ssq, row);
;                 u32x4 w; unsigned pk[4];
; #pragma unroll
;                 for (int n = 0; n < 2; ++n) { const f32x4 g = acc[ai][0][m][n] * rs, up = acc[ai][1][m][n] * rs;
;                     pk[2 * n] = cvt_pk_bf16(fsilu(g[0]) * up[0], fsilu(g[1]) * up[1]); pk[2 * n + 1] = cvt_pk_bf16(fsilu(g[2]) * up[2], fsilu(g[3]) * up[3]); }
;                 w.x = pk[0]; w.y = pk[1]; w.z = pk[2]; w.w = pk[3];
;                 st_wt16(H + (size_t)row * ldh + col0, w); }
	v_pk_add_f32 v[184:185], v[184:185], v[192:193] op_sel_hi:[1,0]
	v_pk_add_f32 v[186:187], v[186:187], v[192:193] op_sel_hi:[1,0]
	v_rcp_f32_e32 v184, v184
	v_rcp_f32_e32 v185, v185
	v_rcp_f32_e32 v186, v186
	v_rcp_f32_e32 v187, v187
	v_pk_mul_f32 v[28:29], v[28:29], v[190:191] op_sel_hi:[1,0]
	v_pk_mul_f32 v[30:31], v[30:31], v[190:191] op_sel_hi:[1,0]
	v_pk_mul_f32 v[28:29], v[28:29], v[184:185]
	v_pk_mul_f32 v[30:31], v[30:31], v[186:187]
	v_pk_mul_f32 v[184:185], v[24:25], v[188:189] op_sel_hi:[1,0]
	v_pk_mul_f32 v[186:187], v[26:27], v[188:189] op_sel_hi:[1,0]
	v_pk_mul_f32 v[24:25], v[24:25], v[16:17]
	v_exp_f32_e32 v184, v184
	v_exp_f32_e32 v185, v185
	v_exp_f32_e32 v186, v186
	v_exp_f32_e32 v187, v187
	v_pk_mul_f32 v[26:27], v[26:27], v[18:19]
	v_pk_add_f32 v[184:185], v[184:185], v[192:193] op_sel_hi:[1,0]
	v_pk_add_f32 v[186:187], v[186:187], v[192:193] op_sel_hi:[1,0]
	v_rcp_f32_e32 v184, v184
	v_rcp_f32_e32 v185, v185
	v_rcp_f32_e32 v186, v186
	v_rcp_f32_e32 v187, v187
	v_pk_mul_f32 v[24:25], v[24:25], v[190:191] op_sel_hi:[1,0]
	v_pk_mul_f32 v[26:27], v[26:27], v[190:191] op_sel_hi:[1,0]
	v_pk_mul_f32 v[24:25], v[24:25], v[184:185]
	v_pk_mul_f32 v[26:27], v[26:27], v[186:187]
	v_cvt_pk_bf16_f32 v16, v28, v29
	v_cvt_pk_bf16_f32 v17, v30, v31
	v_cvt_pk_bf16_f32 v18, v24, v25
	v_cvt_pk_bf16_f32 v19, v26, v27
	s_nop 0
	global_store_dwordx4 v[32:33], v[16:19], off
	s_nop 1
	s_andn2_b64 vcc, exec, s[4:5]
	v_add_u32_e32 v17, 0xb0, v144
	s_mov_b64 s[4:5], -1
	v_fmamk_f32 v16, v182, 0x3a800000, v158
	v_mul_f32_e32 v18, 0x4b800000, v16
	v_cmp_gt_f32_e64 s[6:7], s77, v16
	s_nop 1
	v_cndmask_b32_e64 v16, v16, v18, s[6:7]
	v_rsq_f32_e32 v18, v16
	v_mad_i64_i32 v[16:17], s[34:35], v17, s79, v[146:147]
	v_lshl_add_u64 v[16:17], v[16:17], 0, v[148:149]
	v_mul_f32_e32 v19, 0x45800000, v18
	v_cndmask_b32_e64 v18, v18, v19, s[6:7]
	v_mul_f32_e32 v188, 0xbfb8aa3b, v18
	v_mul_f32_e32 v190, v18, v18
	v_pk_mul_f32 v[184:185], v[12:13], v[188:189] op_sel_hi:[1,0]
	v_pk_mul_f32 v[186:187], v[14:15], v[188:189] op_sel_hi:[1,0]
	v_pk_mul_f32 v[12:13], v[12:13], v[4:5]
	v_exp_f32_e32 v184, v184
	v_exp_f32_e32 v185, v185
	v_exp_f32_e32 v186, v186
	v_exp_f32_e32 v187, v187
	v_pk_mul_f32 v[14:15], v[14:15], v[6:7]
	v_pk_add_f32 v[184:185], v[184:185], v[192:193] op_sel_hi:[1,0]
	v_pk_add_f32 v[186:187], v[186:187], v[192:193] op_sel_hi:[1,0]
	v_rcp_f32_e32 v184, v184
	v_rcp_f32_e32 v185, v185
	v_rcp_f32_e32 v186, v186
	v_rcp_f32_e32 v187, v187
	v_pk_mul_f32 v[12:13], v[12:13], v[190:191] op_sel_hi:[1,0]
	v_pk_mul_f32 v[14:15], v[14:15], v[190:191] op_sel_hi:[1,0]
	v_pk_mul_f32 v[12:13], v[12:13], v[184:185]
	v_pk_mul_f32 v[14:15], v[14:15], v[186:187]
	v_pk_mul_f32 v[184:185], v[8:9], v[188:189] op_sel_hi:[1,0]
	v_pk_mul_f32 v[186:187], v[10:11], v[188:189] op_sel_hi:[1,0]
	v_pk_mul_f32 v[8:9], v[8:9], v[0:1]
	v_exp_f32_e32 v184, v184
	v_exp_f32_e32 v185, v185
	v_exp_f32_e32 v186, v186
	v_exp_f32_e32 v187, v187
	v_pk_mul_f32 v[10:11], v[10:11], v[2:3]
	v_pk_add_f32 v[184:185], v[184:185], v[192:193] op_sel_hi:[1,0]
	v_pk_add_f32 v[186:187], v[186:187], v[192:193] op_sel_hi:[1,0]
	v_rcp_f32_e32 v184, v184
	v_rcp_f32_e32 v185, v185
	v_rcp_f32_e32 v186, v186
	v_rcp_f32_e32 v187, v187
	v_pk_mul_f32 v[8:9], v[8:9], v[190:191] op_sel_hi:[1,0]
	v_pk_mul_f32 v[10:11], v[10:11], v[190:191] op_sel_hi:[1,0]
	v_pk_mul_f32 v[8:9], v[8:9], v[184:185]
	v_pk_mul_f32 v[10:11], v[10:11], v[186:187]
	v_cvt_pk_bf16_f32 v0, v12, v13
	v_cvt_pk_bf16_f32 v1, v14, v15
	v_cvt_pk_bf16_f32 v2, v8, v9
	v_cvt_pk_bf16_f32 v3, v10, v11
	s_nop 0
	global_store_dwordx4 v[16:17], v[0:3], off
	s_cbranch_vccnz .LBB0_1267
	s_andn2_b64 vcc, exec, s[10:11]
	s_cbranch_vccnz .LBB0_1266
	s_barrier
	s_branch .LBB0_1266
